# P0a: S5 discretisation spread over workgroups 192-255 (tau loop split, Bbar part with 16-byte accesses) together with the up-front silu staging loads
# speedup vs baseline: 1.0053x; 1.0053x over previous
.LBB0_16:
	s_or_b64 exec, exec, s[12:13]
	s_add_i32 s6, s38, 0xfffe8000
	s_cmpk_gt_i32 s64, 0xc0
	s_cselect_b64 s[0:1], -1, 0
	s_and_b64 s[4:5], s[0:1], exec
	s_cselect_b32 s4, s6, s38
	s_and_b32 s4, s4, 0xfff
	s_cmpk_lt_i32 s64, 0xc1
	v_add_u32_e32 v7, s4, v1
	s_cselect_b64 s[4:5], -1, 0
	s_cmpk_gt_i32 s2, 0xbf
	s_cselect_b64 s[6:7], -1, 0
	s_or_b64 s[4:5], s[6:7], s[4:5]
	s_movk_i32 s6, 0x1000
	v_cmp_gt_i32_e32 vcc, s6, v7
	v_and_b32_e32 v34, 63, v1
	s_and_b64 s[4:5], s[4:5], vcc
	s_and_saveexec_b64 s[12:13], s[4:5]
	s_cbranch_execz .LBB0_41
	s_lshl_b32 s4, s64, 9
	s_add_i32 s5, s4, 0xfffe8000
	s_and_b64 s[0:1], s[0:1], exec
	s_mov_b32 s18, 0x6dc9c883
	s_mov_b32 s20, 0x54442d18
	s_cselect_b32 s26, s5, s4
	v_mov_b32_e32 v3, 0
	s_mov_b64 s[14:15], 0
	s_mov_b32 s27, 0x3fb8aa3b
	s_mov_b32 s28, 0xc2ce8ed0
	s_mov_b32 s29, 0x42b17218
	v_mov_b32_e32 v18, 0x7f800000
	s_mov_b64 s[16:17], 0x6040004
	s_mov_b32 s19, 0x3fc45f30
	s_mov_b32 s21, 0xc01921fb
	s_brev_b32 s30, 18
	s_mov_b32 s31, 0xfe5163ab
	s_mov_b32 s34, 0x3c439041
	s_mov_b32 s35, 0xdb629599
	s_mov_b32 s36, 0xf534ddc0
	s_mov_b32 s37, 0xfc2757d1
	s_mov_b32 s39, 0x4e441529
	s_mov_b32 s40, 0xa2f9836e
	s_mov_b32 s41, 0x3fc90fda
	s_mov_b32 s42, 0x3f22f983
	s_mov_b32 s43, 0xbfc90fda
	v_mov_b32_e32 v19, 0x3c0881c4
	v_mov_b32_e32 v20, 0xbab64f3b
	s_brev_b32 s44, 1
	s_movk_i32 s45, 0x1f8
	v_mov_b32_e32 v21, 0x3ab69700
	s_mov_b32 s46, 0x43000000
	s_mov_b32 s47, 0x42b17217
	s_mov_b32 s48, 0xc1880000
	s_mov_b64 s[22:23], 0x60c4000
	s_mov_b32 s49, 0x60c4000
	s_movk_i32 s50, 0xfff
	v_not_b32_e32 v22, 63
	v_not_b32_e32 v23, 31
	v_mov_b32_e32 v24, 0x7fc00000
	v_mov_b32_e32 v25, 0x7f000000
	s_branch .LBB0_19
.LBB0_18:
	s_or_b64 exec, exec, s[0:1]
	v_mul_f32_e32 v30, v28, v28
	v_fmamk_f32 v31, v30, 0xb94c1982, v19
	v_fmaak_f32 v31, v30, v31, 0xbe2aaa9d
	v_mul_f32_e32 v31, v30, v31
	v_fmac_f32_e32 v28, v28, v31
	v_fmamk_f32 v31, v30, 0x37d75334, v20
	v_fmaak_f32 v31, v30, v31, 0x3d2aabf7
	v_fmaak_f32 v31, v30, v31, 0xbf000004
	v_fma_f32 v30, v30, v31, 1.0
	v_and_b32_e32 v31, 1, v17
	v_cmp_eq_u32_e32 vcc, 0, v31
	v_lshlrev_b32_e32 v17, 30, v17
	v_xor_b32_e32 v14, v14, v11
	v_cndmask_b32_e32 v28, v30, v28, vcc
	v_cmp_class_f32_e64 vcc, v11, s45
	v_mul_f32_e32 v11, 0x3fb8aa3b, v9
	v_and_b32_e32 v17, 0x80000000, v17
	v_rndne_f32_e32 v11, v11
	v_xor_b32_e32 v14, v14, v17
	v_fmamk_f32 v17, v11, 0xbf317218, v9
	v_fmac_f32_e32 v17, 0x3102e308, v11
	v_xor_b32_e32 v14, v14, v28
	v_fmamk_f32 v28, v17, 0x395133b1, v21
	v_fmaak_f32 v28, v17, v28, 0x3c0887f9
	v_fmaak_f32 v28, v17, v28, 0x3d2aaa81
	v_cvt_i32_f32_e32 v30, v11
	v_fmaak_f32 v28, v17, v28, 0x3e2aaaab
	v_fma_f32 v28, v17, v28, 0.5
	v_mul_f32_e32 v28, v17, v28
	v_cndmask_b32_e32 v14, v24, v14, vcc
	v_fmac_f32_e32 v17, v17, v28
	v_ldexp_f32 v28, 1.0, v30
	v_cmp_eq_f32_e32 vcc, s46, v11
	s_mov_b64 s[0:1], s[78:79]
	s_load_dwordx2 s[4:5], s[0:1], 0x100
	v_cndmask_b32_e32 v11, v28, v25, vcc
	v_add_f32_e32 v28, -1.0, v11
	v_fmac_f32_e32 v28, v11, v17
	s_mov_b64 s[0:1], s[78:79]
	v_add_f32_e32 v11, v28, v28
	s_mov_b64 s[6:7], s[78:79]
	v_cndmask_b32_e32 v11, v28, v11, vcc
	v_cmp_nlt_f32_e32 vcc, s47, v9
	s_load_dwordx2 s[0:1], s[0:1], 0x60
	s_load_dwordx2 s[6:7], s[6:7], 0x68
	v_cndmask_b32_e32 v11, v18, v11, vcc
	v_cmp_ngt_f32_e32 vcc, s48, v9
	v_mul_f32_e32 v28, v16, v16
	v_fmamk_f32 v32, v28, 0xb94c1982, v19
	v_cndmask_b32_e32 v17, -1.0, v11, vcc
	v_ashrrev_i32_e32 v11, 31, v10
	v_lshlrev_b64 v[10:11], 10, v[10:11]
	v_or3_b32 v9, 0, v11, 0
	v_or3_b32 v8, v8, v10, v34
	v_lshlrev_b64 v[10:11], 6, v[8:9]
	s_waitcnt lgkmcnt(0)
	v_lshl_add_u64 v[8:9], s[0:1], 0, v[10:11]
	v_lshl_add_u64 v[10:11], s[6:7], 0, v[10:11]
	global_load_dwordx4 v[176:179], v[8:9], off
	global_load_dwordx4 v[180:183], v[8:9], off offset:16
	global_load_dwordx4 v[184:187], v[8:9], off offset:32
	global_load_dwordx4 v[188:191], v[8:9], off offset:48
	global_load_dwordx4 v[192:195], v[10:11], off
	global_load_dwordx4 v[196:199], v[10:11], off offset:16
	global_load_dwordx4 v[200:203], v[10:11], off offset:32
	global_load_dwordx4 v[204:207], v[10:11], off offset:48
	v_fmaak_f32 v32, v28, v32, 0xbe2aaa9d
	v_mul_f32_e32 v32, v28, v32
	v_fmac_f32_e32 v16, v16, v32
	v_fmamk_f32 v32, v28, 0x37d75334, v20
	v_fmaak_f32 v32, v28, v32, 0x3d2aabf7
	v_fmaak_f32 v32, v28, v32, 0xbf000004
	v_fma_f32 v28, v28, v32, 1.0
	v_and_b32_e32 v32, 1, v15
	v_cmp_eq_u32_e32 vcc, 0, v32
	v_lshlrev_b32_e32 v15, 30, v15
	v_lshl_add_u64 v[4:5], v[4:5], 2, s[4:5]
	v_cndmask_b32_e64 v16, -v16, v28, vcc
	v_bitop3_b32 v15, v15, v16, s44 bitop3:0x6c
	v_cmp_class_f32_e64 vcc, v12, s45
	v_add_f32_e32 v16, v14, v14
	v_mul_f32_e32 v14, v14, v16
	v_cndmask_b32_e32 v15, v24, v15, vcc
	v_mul_f32_e32 v16, v29, v29
	v_fma_f32 v14, v17, v15, -v14
	v_add_f32_e32 v15, 1.0, v17
	v_fmamk_f32 v17, v16, 0xb94c1982, v19
	v_fmaak_f32 v17, v16, v17, 0xbe2aaa9d
	v_mul_f32_e32 v17, v16, v17
	v_fmac_f32_e32 v29, v29, v17
	v_fmamk_f32 v17, v16, 0x37d75334, v20
	v_fmaak_f32 v17, v16, v17, 0x3d2aabf7
	v_fmaak_f32 v17, v16, v17, 0xbf000004
	v_fma_f32 v16, v16, v17, 1.0
	v_and_b32_e32 v17, 1, v2
	v_lshlrev_b32_e32 v2, 30, v2
	v_cmp_eq_u32_e64 s[0:1], 0, v17
	v_and_b32_e32 v2, 0x80000000, v2
	v_xor_b32_e32 v12, v13, v12
	v_cndmask_b32_e64 v16, v16, v29, s[0:1]
	v_xor_b32_e32 v2, v12, v2
	v_xor_b32_e32 v2, v2, v16
	v_cndmask_b32_e32 v2, v24, v2, vcc
	v_mul_f32_e32 v2, v15, v2
	v_mul_f32_e32 v12, v27, v27
	v_mul_f32_e32 v13, v27, v2
	v_fmac_f32_e32 v12, v26, v26
	v_fmac_f32_e32 v13, v26, v14
	v_mul_f32_e32 v14, v27, v14
	v_fma_f32 v2, v26, v2, -v14
	v_rcp_f32_e32 v15, v12
	s_nop 0
	v_mul_f32_e32 v15, v13, v15
	v_add_u32_e32 v7, s26, v7
	v_rcp_f32_e32 v13, v12
	s_nop 0
	v_mul_f32_e32 v14, v2, v13
	v_lshlrev_b32_e32 v2, 7, v6
	v_lshl_add_u64 v[4:5], v[4:5], 0, v[2:3]
	v_add_co_u32_e32 v12, vcc, s49, v4
	v_addc_co_u32_e32 v13, vcc, 0, v5, vcc
	v_lshl_add_u64 v[4:5], v[4:5], 0, s[22:23]
	v_cmp_lt_i32_e32 vcc, s50, v7
	s_or_b64 s[14:15], vcc, s[14:15]
	s_waitcnt vmcnt(0)
	v_mul_f32_e32 v124, v14, v192
	v_mul_f32_e32 v125, v14, v176
	v_mul_f32_e32 v126, v14, v193
	v_mul_f32_e32 v127, v14, v177
	v_fma_f32 v124, v15, v176, -v124
	v_fmac_f32_e32 v125, v15, v192
	v_fma_f32 v126, v15, v177, -v126
	v_fmac_f32_e32 v127, v15, v193
	global_store_dwordx4 v[4:5], v[124:127], off
	v_mul_f32_e32 v128, v14, v194
	v_mul_f32_e32 v129, v14, v178
	v_mul_f32_e32 v130, v14, v195
	v_mul_f32_e32 v131, v14, v179
	v_fma_f32 v128, v15, v178, -v128
	v_fmac_f32_e32 v129, v15, v194
	v_fma_f32 v130, v15, v179, -v130
	v_fmac_f32_e32 v131, v15, v195
	global_store_dwordx4 v[4:5], v[128:131], off offset:16
	v_mul_f32_e32 v132, v14, v196
	v_mul_f32_e32 v133, v14, v180
	v_mul_f32_e32 v134, v14, v197
	v_mul_f32_e32 v135, v14, v181
	v_fma_f32 v132, v15, v180, -v132
	v_fmac_f32_e32 v133, v15, v196
	v_fma_f32 v134, v15, v181, -v134
	v_fmac_f32_e32 v135, v15, v197
	global_store_dwordx4 v[4:5], v[132:135], off offset:32
	v_mul_f32_e32 v136, v14, v198
	v_mul_f32_e32 v137, v14, v182
	v_mul_f32_e32 v138, v14, v199
	v_mul_f32_e32 v139, v14, v183
	v_fma_f32 v136, v15, v182, -v136
	v_fmac_f32_e32 v137, v15, v198
	v_fma_f32 v138, v15, v183, -v138
	v_fmac_f32_e32 v139, v15, v199
	global_store_dwordx4 v[4:5], v[136:139], off offset:48
	v_mul_f32_e32 v124, v14, v200
	v_mul_f32_e32 v125, v14, v184
	v_mul_f32_e32 v126, v14, v201
	v_mul_f32_e32 v127, v14, v185
	v_fma_f32 v124, v15, v184, -v124
	v_fmac_f32_e32 v125, v15, v200
	v_fma_f32 v126, v15, v185, -v126
	v_fmac_f32_e32 v127, v15, v201
	global_store_dwordx4 v[4:5], v[124:127], off offset:64
	v_mul_f32_e32 v128, v14, v202
	v_mul_f32_e32 v129, v14, v186
	v_mul_f32_e32 v130, v14, v203
	v_mul_f32_e32 v131, v14, v187
	v_fma_f32 v128, v15, v186, -v128
	v_fmac_f32_e32 v129, v15, v202
	v_fma_f32 v130, v15, v187, -v130
	v_fmac_f32_e32 v131, v15, v203
	global_store_dwordx4 v[4:5], v[128:131], off offset:80
	v_mul_f32_e32 v132, v14, v204
	v_mul_f32_e32 v133, v14, v188
	v_mul_f32_e32 v134, v14, v205
	v_mul_f32_e32 v135, v14, v189
	v_fma_f32 v132, v15, v188, -v132
	v_fmac_f32_e32 v133, v15, v204
	v_fma_f32 v134, v15, v189, -v134
	v_fmac_f32_e32 v135, v15, v205
	global_store_dwordx4 v[4:5], v[132:135], off offset:96
	v_mul_f32_e32 v136, v14, v206
	v_mul_f32_e32 v137, v14, v190
	v_mul_f32_e32 v138, v14, v207
	v_mul_f32_e32 v139, v14, v191
	v_fma_f32 v136, v15, v190, -v136
	v_fmac_f32_e32 v137, v15, v206
	v_fma_f32 v138, v15, v191, -v138
	v_fmac_f32_e32 v139, v15, v207
	global_store_dwordx4 v[4:5], v[136:139], off offset:112
	s_andn2_b64 exec, exec, s[14:15]
	s_cbranch_execz .LBB0_41
.LBB0_19:
	v_bfe_u32 v2, v7, 6, 1
	v_ashrrev_i32_e32 v10, 11, v7
	s_mov_b64 s[0:1], s[78:79]
	v_lshl_or_b32 v4, v10, 1, v2
	v_bfe_u32 v6, v7, 7, 4
	s_load_dwordx2 s[0:1], s[0:1], 0x48
	v_ashrrev_i32_e32 v5, 31, v4
	v_lshlrev_b64 v[12:13], 10, v[4:5]
	v_lshlrev_b32_e32 v8, 6, v6
	v_or_b32_e32 v5, v12, v8
	v_or_b32_e32 v12, v5, v34
	v_lshlrev_b64 v[12:13], 2, v[12:13]
	s_waitcnt lgkmcnt(0)
	v_lshl_add_u64 v[14:15], s[0:1], 0, v[12:13]
	s_mov_b64 s[0:1], s[78:79]
	global_load_dword v26, v[14:15], off
	s_load_dwordx2 s[0:1], s[0:1], 0x50
	v_lshl_or_b32 v4, v4, 4, v6
	v_ashrrev_i32_e32 v5, 31, v4
	v_lshlrev_b32_e32 v6, 7, v6
	v_lshlrev_b32_e32 v2, 6, v2
	s_waitcnt lgkmcnt(0)
	v_lshl_add_u64 v[12:13], s[0:1], 0, v[12:13]
	s_mov_b64 s[0:1], s[78:79]
	global_load_dword v27, v[12:13], off
	s_mov_b64 s[0:1], s[78:79]
	s_load_dwordx2 s[0:1], s[0:1], 0x58
	v_or3_b32 v6, v6, v2, v34
	v_mul_hi_u32_u24_e32 v15, 0x108, v6
	v_mul_u32_u24_e32 v14, 0x108, v6
	s_sub_i32 s51, s2, 0xc0
	s_lshr_b32 s51, s51, 3
	v_cvt_f64_u32_e32 v[12:13], s51
	s_waitcnt lgkmcnt(0)
	v_lshl_add_u64 v[4:5], v[4:5], 2, s[0:1]
	global_load_dword v9, v[4:5], off
	s_mov_b64 s[0:1], s[78:79]
	s_load_dwordx2 s[0:1], s[0:1], 0x100
	v_mul_hi_i32_i24_e32 v5, 0x71000, v10
	v_mul_i32_i24_e32 v4, 0x71000, v10
	v_lshl_add_u64 v[14:15], v[4:5], 2, v[14:15]
	s_waitcnt lgkmcnt(0)
	v_lshl_add_u64 v[14:15], s[0:1], 0, v[14:15]
	v_lshl_add_u64 v[14:15], v[14:15], 0, s[16:17]
	v_lshlrev_b32_e64 v2, 3, s51
	v_lshl_add_u64 v[14:15], v[14:15], 0, v[2:3]
	s_waitcnt vmcnt(0)
	v_mul_f32_e32 v2, 0x3fb8aa3b, v9
	v_fma_f32 v11, v9, s27, -v2
	v_rndne_f32_e32 v16, v2
	v_fmac_f32_e32 v11, 0x32a5705f, v9
	v_sub_f32_e32 v2, v2, v16
	v_add_f32_e32 v2, v2, v11
	v_cvt_i32_f32_e32 v28, v16
	v_exp_f32_e32 v2, v2
	v_cmp_ngt_f32_e32 vcc, s28, v9
	v_cvt_f64_f32_e32 v[16:17], v27
	v_ldexp_f32 v2, v2, v28
	v_cndmask_b32_e32 v2, 0, v2, vcc
	v_cmp_nlt_f32_e32 vcc, s29, v9
	s_nop 1
	v_cndmask_b32_e32 v11, v18, v2, vcc
	v_cvt_f64_f32_e32 v[28:29], v11
	v_mul_f32_e32 v9, v26, v11
	v_mul_f64 v[16:17], v[16:17], v[28:29]
	s_branch .LBB0_21
.LBB0_20:
	s_or_b64 exec, exec, s[0:1]
	v_mul_f32_e32 v2, v35, v35
	v_fmamk_f32 v30, v2, 0xb94c1982, v19
	v_fmaak_f32 v30, v2, v30, 0xbe2aaa9d
	v_mul_f32_e32 v30, v2, v30
	v_fmac_f32_e32 v35, v35, v30
	v_fmamk_f32 v30, v2, 0x37d75334, v20
	v_fmaak_f32 v30, v2, v30, 0x3d2aabf7
	v_fmaak_f32 v30, v2, v30, 0xbf000004
	v_fma_f32 v2, v2, v30, 1.0
	v_and_b32_e32 v30, 1, v33
	v_cmp_eq_u32_e64 s[0:1], 0, v30
	v_lshlrev_b32_e32 v30, 30, v33
	v_and_b32_e32 v30, 0x80000000, v30
	v_xor_b32_e32 v28, v29, v28
	v_cndmask_b32_e64 v2, v2, v35, s[0:1]
	v_xor_b32_e32 v28, v28, v30
	v_xor_b32_e32 v2, v28, v2
	v_cndmask_b32_e32 v2, v24, v2, vcc
	v_mul_f32_e32 v2, v32, v2
	s_add_i32 s51, s51, 8
	global_store_dword v[14:15], v2, off
	v_add_f64 v[12:13], v[12:13], 4.0
	v_add_f64 v[12:13], v[12:13], 4.0
	s_cmp_ge_u32 s51, 33
	v_lshl_add_u64 v[14:15], v[14:15], 0, 64
	s_cbranch_scc1 .LBB0_29

.LBB0_29:
	s_cmpk_lt_u32 s2, 0xf8
	s_cbranch_scc1 .LBB0_41
	v_mul_f32_e32 v12, v27, v11
	v_mul_f32_e32 v11, 0.5, v12
	v_and_b32_e32 v14, 0x7fffffff, v11
	v_cmp_nlt_f32_e64 s[0:1], |v11|, s30
	s_and_saveexec_b64 s[4:5], s[0:1]
	s_xor_b64 s[8:9], exec, s[4:5]
	s_cbranch_execz .LBB0_31
	v_lshrrev_b32_e32 v2, 23, v14
	v_add_u32_e32 v2, 0xffffff88, v2
	v_cmp_lt_u32_e32 vcc, 63, v2
	s_nop 1
	v_cndmask_b32_e32 v13, 0, v22, vcc
	v_add_u32_e32 v2, v13, v2
	v_cmp_lt_u32_e64 s[0:1], 31, v2
	s_nop 1
	v_cndmask_b32_e64 v13, 0, v23, s[0:1]
	v_add_u32_e32 v2, v13, v2
	v_cmp_lt_u32_e64 s[4:5], 31, v2
	s_nop 1
	v_cndmask_b32_e64 v13, 0, v23, s[4:5]
	v_add_u32_e32 v13, v13, v2
	v_and_b32_e32 v2, 0x7fffff, v14
	v_or_b32_e32 v15, 0x800000, v2
	v_mad_u64_u32 v[16:17], s[6:7], v15, s31, 0
	v_mov_b32_e32 v2, v17
	v_mad_u64_u32 v[28:29], s[6:7], v15, s34, v[2:3]
	v_mov_b32_e32 v2, v29
	v_mad_u64_u32 v[30:31], s[6:7], v15, s35, v[2:3]
	v_mov_b32_e32 v2, v31
	v_mad_u64_u32 v[32:33], s[6:7], v15, s36, v[2:3]
	v_mov_b32_e32 v2, v33
	v_mad_u64_u32 v[36:37], s[6:7], v15, s37, v[2:3]
	v_mov_b32_e32 v2, v37
	v_mad_u64_u32 v[38:39], s[6:7], v15, s39, v[2:3]
	v_mov_b32_e32 v2, v39
	v_mad_u64_u32 v[40:41], s[6:7], v15, s40, v[2:3]
	v_cndmask_b32_e32 v17, v38, v32, vcc
	v_cndmask_b32_e32 v2, v40, v36, vcc
	v_cndmask_b32_e32 v29, v41, v38, vcc
	v_cndmask_b32_e64 v15, v2, v17, s[0:1]
	v_cndmask_b32_e64 v2, v29, v2, s[0:1]
	v_cndmask_b32_e32 v29, v36, v30, vcc
	v_cndmask_b32_e64 v17, v17, v29, s[0:1]
	v_sub_u32_e32 v31, 32, v13
	v_cmp_eq_u32_e64 s[6:7], 0, v13
	v_cndmask_b32_e32 v13, v32, v28, vcc
	v_cndmask_b32_e64 v2, v2, v15, s[4:5]
	v_cndmask_b32_e64 v15, v15, v17, s[4:5]
	v_cndmask_b32_e64 v28, v29, v13, s[0:1]
	v_alignbit_b32 v33, v2, v15, v31
	v_cndmask_b32_e64 v17, v17, v28, s[4:5]
	v_cndmask_b32_e64 v2, v33, v2, s[6:7]
	v_alignbit_b32 v29, v15, v17, v31
	v_cndmask_b32_e32 v16, v30, v16, vcc
	v_cndmask_b32_e64 v15, v29, v15, s[6:7]
	v_bfe_u32 v33, v2, 29, 1
	v_cndmask_b32_e64 v13, v13, v16, s[0:1]
	v_alignbit_b32 v29, v2, v15, 30
	v_sub_u32_e32 v35, 0, v33
	v_cndmask_b32_e64 v13, v28, v13, s[4:5]
	v_xor_b32_e32 v29, v29, v35
	v_alignbit_b32 v16, v17, v13, v31
	v_cndmask_b32_e64 v16, v16, v17, s[6:7]
	v_ffbh_u32_e32 v17, v29
	v_alignbit_b32 v15, v15, v16, 30
	v_min_u32_e32 v17, 32, v17
	v_alignbit_b32 v13, v16, v13, 30
	v_xor_b32_e32 v15, v15, v35
	v_sub_u32_e32 v28, 31, v17
	v_xor_b32_e32 v13, v13, v35
	v_alignbit_b32 v29, v29, v15, v28
	v_alignbit_b32 v13, v15, v13, v28
	v_alignbit_b32 v15, v29, v13, 9
	v_ffbh_u32_e32 v16, v15
	v_min_u32_e32 v16, 32, v16
	v_lshrrev_b32_e32 v32, 29, v2
	v_not_b32_e32 v28, v16
	v_alignbit_b32 v13, v15, v13, v28
	v_lshlrev_b32_e32 v15, 31, v32
	v_or_b32_e32 v28, 0x33000000, v15
	v_add_lshl_u32 v16, v16, v17, 23
	v_lshrrev_b32_e32 v13, 9, v13
	v_sub_u32_e32 v16, v28, v16
	v_or_b32_e32 v15, 0.5, v15
	v_lshlrev_b32_e32 v17, 23, v17
	v_or_b32_e32 v13, v16, v13
	v_lshrrev_b32_e32 v16, 9, v29
	v_sub_u32_e32 v15, v15, v17
	v_or_b32_e32 v15, v16, v15
	v_mul_f32_e32 v16, 0x3fc90fda, v15
	v_fma_f32 v17, v15, s41, -v16
	v_fmac_f32_e32 v17, 0x33a22168, v15
	v_fmac_f32_e32 v17, 0x3fc90fda, v13
	v_lshrrev_b32_e32 v2, 30, v2
	v_add_f32_e32 v28, v16, v17
	v_add_u32_e32 v17, v33, v2
